# v30_midtail
# baseline (speedup 1.0000x reference)
; __device__ __forceinline__ float bf_lo(unsigned w) { return __uint_as_float(w << 16); }
; __device__ __forceinline__ float bf_hi(unsigned w) { return __uint_as_float(w & 0xffff0000u); }
; __device__ __forceinline__ void phase_mid(const Params& p, int gw, int NGW, int lane) {
;     ...
;     for (int row = gw; row < MT; row += NGW) {
;         const float r1 = rsqrtf(wave_sum(SSQ[(size_t)lane * MT + row]) * (1.f / DM) + EPSN);
;         const u32x2* mr = (const u32x2*)(MO + (size_t)row * DM) + lane; const f32x4* xr = (const f32x4*)(x + (size_t)row * DM) + lane;
;         const f32x4* g1p = g1 + lane; const f32x4* g2p = g2 + lane;
;         asm volatile("" : "+v"(g1p), "+v"(g2p), "+v"(mr), "+v"(xr));
;         f32x4 h[16]; float ss = 0.f;
; #pragma unroll
;         for (int j = 0; j < 16; ++j) { const u32x2 mw = mr[64 * j]; const f32x4 mo = {bf_lo(mw.x), bf_hi(mw.x), bf_lo(mw.y), bf_hi(mw.y)}; h[j] = xr[64 * j] + mo * r1 * g1p[64 * j]; ss += (h[j][0] * h[j][0] + h[j][1] * h[j][1]) + (h[j][2] * h[j][2] + h[j][3] * h[j][3]); }
.LBB0_711:
	global_load_dword v26, v[10:11], off
	v_lshl_add_u64 v[20:21], v[0:1], 0, s[6:7]
	v_mov_b64_e32 v[14:15], v[4:5]
	v_mov_b64_e32 v[18:19], v[12:13]
	v_mov_b64_e32 v[16:17], v[2:3]
	flat_load_dwordx4 v[28:31], v[18:19]
	flat_load_dwordx4 v[32:35], v[18:19] offset:1024
	flat_load_dwordx4 v[36:39], v[16:17]
	flat_load_dwordx4 v[40:43], v[16:17] offset:1024
	flat_load_dwordx2 v[66:67], v[20:21]
	flat_load_dwordx2 v[68:69], v[20:21] offset:512
	flat_load_dwordx2 v[70:71], v[20:21] offset:1024
	flat_load_dwordx2 v[72:73], v[20:21] offset:1536
	flat_load_dwordx4 v[46:49], v[18:19] offset:2048
	flat_load_dwordx4 v[50:53], v[18:19] offset:3072
	flat_load_dwordx4 v[54:57], v[16:17] offset:2048
	flat_load_dwordx4 v[58:61], v[16:17] offset:3072
	v_add_co_u32_e32 v92, vcc, s9, v18
	flat_load_dwordx2 v[168:169], v[20:21] offset:2048
	flat_load_dwordx2 v[170:171], v[20:21] offset:2560
	flat_load_dwordx2 v[172:173], v[20:21] offset:3072
	flat_load_dwordx2 v[180:181], v[20:21] offset:3584
	v_addc_co_u32_e32 v93, vcc, 0, v19, vcc
	v_add_co_u32_e32 v100, vcc, s9, v16
	v_lshl_add_u64 v[24:25], v[6:7], 0, s[6:7]
	s_nop 0
	v_addc_co_u32_e32 v101, vcc, 0, v17, vcc
	v_add_co_u32_e32 v20, vcc, s9, v20
	v_lshl_add_u64 v[22:23], v[8:9], 0, s[6:7]
	s_nop 0
	v_addc_co_u32_e32 v21, vcc, 0, v21, vcc
	v_add_co_u32_e32 v124, vcc, s3, v18
	s_add_i32 s17, s17, s60
	s_nop 0
	v_addc_co_u32_e32 v125, vcc, 0, v19, vcc
	v_add_co_u32_e32 v132, vcc, s3, v16
	s_add_u32 s6, s6, s12
	s_nop 0
	v_addc_co_u32_e32 v133, vcc, 0, v17, vcc
	v_add_co_u32_e32 v156, vcc, s16, v18
	s_addc_u32 s7, s7, s13
	s_nop 0
	v_addc_co_u32_e32 v157, vcc, 0, v19, vcc
	v_add_co_u32_e32 v164, vcc, s16, v16
	v_lshl_add_u64 v[10:11], v[10:11], 0, s[4:5]
	s_nop 0
	v_addc_co_u32_e32 v165, vcc, 0, v17, vcc
	flat_load_dwordx2 v[182:183], v[20:21]
	flat_load_dwordx2 v[184:185], v[20:21] offset:512
	flat_load_dwordx2 v[186:187], v[20:21] offset:1024
	flat_load_dwordx2 v[188:189], v[20:21] offset:1536
	flat_load_dwordx2 v[190:191], v[20:21] offset:2048
	flat_load_dwordx2 v[194:195], v[20:21] offset:2560
	flat_load_dwordx4 v[16:19], v[92:93]
	flat_load_dwordx4 v[80:83], v[92:93] offset:1024
	flat_load_dwordx4 v[62:65], v[100:101]
	flat_load_dwordx4 v[84:87], v[100:101] offset:1024
	flat_load_dwordx2 v[196:197], v[20:21] offset:3072
	flat_load_dwordx4 v[88:91], v[92:93] offset:2048
	s_nop 0
	flat_load_dwordx4 v[92:95], v[92:93] offset:3072
	s_nop 0
	flat_load_dwordx2 v[20:21], v[20:21] offset:3584
	s_nop 0
	flat_load_dwordx4 v[96:99], v[100:101] offset:2048
	s_nop 0
	flat_load_dwordx4 v[100:103], v[100:101] offset:3072
	s_nop 0
	flat_load_dwordx4 v[104:107], v[124:125]
	flat_load_dwordx4 v[108:111], v[124:125] offset:1024
	flat_load_dwordx4 v[112:115], v[132:133]
	flat_load_dwordx4 v[116:119], v[132:133] offset:1024
	flat_load_dwordx4 v[120:123], v[124:125] offset:2048
	s_nop 0
	flat_load_dwordx4 v[124:127], v[124:125] offset:3072
	s_nop 0
	flat_load_dwordx4 v[128:131], v[132:133] offset:2048
	s_nop 0
	flat_load_dwordx4 v[132:135], v[132:133] offset:3072
	s_nop 0
	flat_load_dwordx4 v[136:139], v[156:157]
	flat_load_dwordx4 v[140:143], v[156:157] offset:1024
	flat_load_dwordx4 v[144:147], v[164:165]
	flat_load_dwordx4 v[148:151], v[164:165] offset:1024
	flat_load_dwordx4 v[152:155], v[156:157] offset:2048
	s_nop 0
	flat_load_dwordx4 v[156:159], v[156:157] offset:3072
	s_nop 0
	flat_load_dwordx4 v[160:163], v[164:165] offset:2048
	s_nop 0
	flat_load_dwordx4 v[164:167], v[164:165] offset:3072
	v_lshl_add_u64 v[12:13], v[12:13], 0, s[14:15]
	s_cmpk_lt_i32 s17, 0x2000
	s_waitcnt vmcnt(0) lgkmcnt(0)
	v_lshlrev_b32_e32 v198, 16, v66
	ds_bpermute_b32 v27, v45, v26
	v_and_b32_e32 v199, 0xffff0000, v66
	v_lshlrev_b32_e32 v66, 16, v67
	v_and_b32_e32 v67, 0xffff0000, v67
	v_lshlrev_b32_e32 v200, 16, v68
	s_waitcnt lgkmcnt(0)
	v_add_f32_e32 v26, v26, v27
	ds_bpermute_b32 v27, v74, v26
	v_and_b32_e32 v201, 0xffff0000, v68
	v_lshlrev_b32_e32 v68, 16, v69
	v_and_b32_e32 v69, 0xffff0000, v69
	v_lshlrev_b32_e32 v202, 16, v70
	s_waitcnt lgkmcnt(0)
	v_add_f32_e32 v26, v26, v27
	ds_bpermute_b32 v27, v75, v26
	v_and_b32_e32 v203, 0xffff0000, v70
	v_lshlrev_b32_e32 v70, 16, v71
	v_and_b32_e32 v71, 0xffff0000, v71
	v_lshlrev_b32_e32 v204, 16, v72
	s_waitcnt lgkmcnt(0)
	v_add_f32_e32 v26, v26, v27
	ds_bpermute_b32 v27, v76, v26
	v_and_b32_e32 v205, 0xffff0000, v72
	v_lshlrev_b32_e32 v72, 16, v73
	v_and_b32_e32 v73, 0xffff0000, v73
	v_lshlrev_b32_e32 v206, 16, v168
	s_waitcnt lgkmcnt(0)
	v_add_f32_e32 v26, v26, v27
	ds_bpermute_b32 v27, v77, v26
	v_and_b32_e32 v207, 0xffff0000, v168
	v_lshlrev_b32_e32 v168, 16, v169
	v_and_b32_e32 v169, 0xffff0000, v169
	v_lshlrev_b32_e32 v208, 16, v170
	s_waitcnt lgkmcnt(0)
	v_add_f32_e32 v26, v26, v27
	ds_bpermute_b32 v27, v78, v26
	v_and_b32_e32 v209, 0xffff0000, v170
	v_lshlrev_b32_e32 v170, 16, v171
	v_and_b32_e32 v171, 0xffff0000, v171
	v_lshlrev_b32_e32 v212, 16, v180
	s_waitcnt lgkmcnt(0)
; __device__ __forceinline__ float bf_lo(unsigned w) { return __uint_as_float(w << 16); }
; __device__ __forceinline__ float bf_hi(unsigned w) { return __uint_as_float(w & 0xffff0000u); }
; __device__ __forceinline__ void phase_mid(const Params& p, int gw, int NGW, int lane) {
;     ...
;         const float r1 = rsqrtf(wave_sum(SSQ[(size_t)lane * MT + row]) * (1.f / DM) + EPSN);
;         const u32x2* mr = (const u32x2*)(MO + (size_t)row * DM) + lane; const f32x4* xr = (const f32x4*)(x + (size_t)row * DM) + lane;
;         const f32x4* g1p = g1 + lane; const f32x4* g2p = g2 + lane;
;         asm volatile("" : "+v"(g1p), "+v"(g2p), "+v"(mr), "+v"(xr));
;         f32x4 h[16]; float ss = 0.f;
; #pragma unroll
;         for (int j = 0; j < 16; ++j) { const u32x2 mw = mr[64 * j]; const f32x4 mo = {bf_lo(mw.x), bf_hi(mw.x), bf_lo(mw.y), bf_hi(mw.y)}; h[j] = xr[64 * j] + mo * r1 * g1p[64 * j]; ss += (h[j][0] * h[j][0] + h[j][1] * h[j][1]) + (h[j][2] * h[j][2] + h[j][3] * h[j][3]); }
	v_add_f32_e32 v26, v26, v27
	v_fmamk_f32 v26, v26, 0x39800000, v79
	v_mul_f32_e32 v27, 0x4b800000, v26
	v_cmp_gt_f32_e32 vcc, s8, v26
	v_and_b32_e32 v213, 0xffff0000, v180
	v_lshlrev_b32_e32 v180, 16, v181
	v_cndmask_b32_e32 v26, v26, v27, vcc
	v_rsq_f32_e32 v26, v26
	v_and_b32_e32 v181, 0xffff0000, v181
	v_lshlrev_b32_e32 v214, 16, v182
	v_and_b32_e32 v215, 0xffff0000, v182
	v_mul_f32_e32 v27, 0x45800000, v26
	v_cndmask_b32_e32 v26, v26, v27, vcc
	v_lshlrev_b32_e32 v182, 16, v183
	v_and_b32_e32 v183, 0xffff0000, v183
	v_lshlrev_b32_e32 v218, 16, v186
	v_and_b32_e32 v219, 0xffff0000, v186
	v_lshlrev_b32_e32 v186, 16, v187
	v_and_b32_e32 v187, 0xffff0000, v187
	v_lshlrev_b32_e32 v220, 16, v188
	v_and_b32_e32 v221, 0xffff0000, v188
	v_lshlrev_b32_e32 v188, 16, v189
	v_and_b32_e32 v189, 0xffff0000, v189
	v_lshlrev_b32_e32 v224, 16, v194
	v_and_b32_e32 v225, 0xffff0000, v194
	v_lshlrev_b32_e32 v194, 16, v195
	v_and_b32_e32 v195, 0xffff0000, v195
	v_lshlrev_b32_e32 v226, 16, v196
	v_and_b32_e32 v227, 0xffff0000, v196
	v_lshlrev_b32_e32 v196, 16, v197
	v_and_b32_e32 v197, 0xffff0000, v197
	v_pk_mul_f32 v[198:199], v[26:27], v[198:199] op_sel_hi:[0,1]
	v_pk_mul_f32 v[66:67], v[26:27], v[66:67] op_sel_hi:[0,1]
	v_pk_mul_f32 v[200:201], v[26:27], v[200:201] op_sel_hi:[0,1]
	v_pk_mul_f32 v[68:69], v[26:27], v[68:69] op_sel_hi:[0,1]
	v_lshlrev_b32_e32 v210, 16, v172
	v_and_b32_e32 v211, 0xffff0000, v172
	v_lshlrev_b32_e32 v172, 16, v173
	v_and_b32_e32 v173, 0xffff0000, v173
	v_lshlrev_b32_e32 v216, 16, v184
	v_and_b32_e32 v217, 0xffff0000, v184
	v_lshlrev_b32_e32 v184, 16, v185
	v_and_b32_e32 v185, 0xffff0000, v185
	v_lshlrev_b32_e32 v222, 16, v190
	v_and_b32_e32 v223, 0xffff0000, v190
	v_lshlrev_b32_e32 v190, 16, v191
	v_and_b32_e32 v191, 0xffff0000, v191
	v_lshlrev_b32_e32 v228, 16, v20
	v_and_b32_e32 v229, 0xffff0000, v20
	v_lshlrev_b32_e32 v20, 16, v21
	v_and_b32_e32 v21, 0xffff0000, v21
	v_pk_mul_f32 v[202:203], v[26:27], v[202:203] op_sel_hi:[0,1]
	v_pk_mul_f32 v[70:71], v[26:27], v[70:71] op_sel_hi:[0,1]
	v_pk_mul_f32 v[204:205], v[26:27], v[204:205] op_sel_hi:[0,1]
	v_pk_mul_f32 v[72:73], v[26:27], v[72:73] op_sel_hi:[0,1]
	v_pk_mul_f32 v[206:207], v[26:27], v[206:207] op_sel_hi:[0,1]
	v_pk_mul_f32 v[168:169], v[26:27], v[168:169] op_sel_hi:[0,1]
	v_pk_mul_f32 v[208:209], v[26:27], v[208:209] op_sel_hi:[0,1]
	v_pk_mul_f32 v[170:171], v[26:27], v[170:171] op_sel_hi:[0,1]
	v_pk_mul_f32 v[212:213], v[26:27], v[212:213] op_sel_hi:[0,1]
	v_pk_mul_f32 v[180:181], v[26:27], v[180:181] op_sel_hi:[0,1]
	v_pk_mul_f32 v[214:215], v[26:27], v[214:215] op_sel_hi:[0,1]
	v_pk_mul_f32 v[182:183], v[26:27], v[182:183] op_sel_hi:[0,1]
	v_pk_mul_f32 v[218:219], v[26:27], v[218:219] op_sel_hi:[0,1]
	v_pk_mul_f32 v[186:187], v[26:27], v[186:187] op_sel_hi:[0,1]
	v_pk_mul_f32 v[220:221], v[26:27], v[220:221] op_sel_hi:[0,1]
	v_pk_mul_f32 v[188:189], v[26:27], v[188:189] op_sel_hi:[0,1]
	v_pk_mul_f32 v[224:225], v[26:27], v[224:225] op_sel_hi:[0,1]
	v_pk_mul_f32 v[194:195], v[26:27], v[194:195] op_sel_hi:[0,1]
	v_pk_mul_f32 v[226:227], v[26:27], v[226:227] op_sel_hi:[0,1]
	v_pk_mul_f32 v[196:197], v[26:27], v[196:197] op_sel_hi:[0,1]
	v_pk_fma_f32 v[232:233], v[38:39], v[66:67], v[30:31]
	v_pk_fma_f32 v[198:199], v[36:37], v[198:199], v[28:29]
	v_pk_fma_f32 v[234:235], v[42:43], v[68:69], v[34:35]
	v_pk_fma_f32 v[200:201], v[40:41], v[200:201], v[32:33]
	v_pk_mul_f32 v[210:211], v[26:27], v[210:211] op_sel_hi:[0,1]
	v_pk_mul_f32 v[172:173], v[26:27], v[172:173] op_sel_hi:[0,1]
	v_pk_mul_f32 v[216:217], v[26:27], v[216:217] op_sel_hi:[0,1]
	v_pk_mul_f32 v[184:185], v[26:27], v[184:185] op_sel_hi:[0,1]
	v_pk_mul_f32 v[222:223], v[26:27], v[222:223] op_sel_hi:[0,1]
	v_pk_mul_f32 v[190:191], v[26:27], v[190:191] op_sel_hi:[0,1]
	v_pk_mul_f32 v[228:229], v[26:27], v[228:229] op_sel_hi:[0,1]
	v_pk_mul_f32 v[230:231], v[26:27], v[20:21] op_sel_hi:[0,1]
	v_pk_fma_f32 v[236:237], v[56:57], v[70:71], v[48:49]
	v_pk_fma_f32 v[202:203], v[54:55], v[202:203], v[46:47]
	v_pk_fma_f32 v[70:71], v[60:61], v[72:73], v[52:53]
	v_pk_fma_f32 v[72:73], v[58:59], v[204:205], v[50:51]
	v_pk_fma_f32 v[66:67], v[64:65], v[168:169], v[18:19]
	v_pk_fma_f32 v[68:69], v[62:63], v[206:207], v[16:17]
	v_pk_fma_f32 v[62:63], v[86:87], v[170:171], v[82:83]
	v_pk_fma_f32 v[64:65], v[84:85], v[208:209], v[80:81]
	v_pk_fma_f32 v[54:55], v[102:103], v[180:181], v[94:95]
	v_pk_fma_f32 v[56:57], v[100:101], v[212:213], v[92:93]
	v_pk_fma_f32 v[50:51], v[114:115], v[182:183], v[106:107]
	v_pk_fma_f32 v[52:53], v[112:113], v[214:215], v[104:105]
	v_pk_fma_f32 v[40:41], v[130:131], v[186:187], v[122:123]
	v_pk_fma_f32 v[42:43], v[128:129], v[218:219], v[120:121]
	v_pk_fma_f32 v[36:37], v[134:135], v[188:189], v[126:127]
	v_pk_fma_f32 v[38:39], v[132:133], v[220:221], v[124:125]
	v_pk_fma_f32 v[28:29], v[150:151], v[194:195], v[142:143]
	v_pk_fma_f32 v[30:31], v[148:149], v[224:225], v[140:141]
	v_pk_fma_f32 v[20:21], v[162:163], v[196:197], v[154:155]
	v_pk_fma_f32 v[26:27], v[160:161], v[226:227], v[152:153]
	v_pk_mul_f32 v[80:81], v[232:233], v[232:233]
	v_pk_mul_f32 v[82:83], v[198:199], v[198:199]
	v_pk_mul_f32 v[84:85], v[234:235], v[234:235]
	v_pk_mul_f32 v[86:87], v[200:201], v[200:201]
	v_pk_fma_f32 v[58:59], v[98:99], v[172:173], v[90:91]
	v_pk_fma_f32 v[60:61], v[96:97], v[210:211], v[88:89]
	v_pk_fma_f32 v[46:47], v[118:119], v[184:185], v[110:111]
	v_pk_fma_f32 v[48:49], v[116:117], v[216:217], v[108:109]
	v_pk_mul_f32 v[90:91], v[66:67], v[66:67]
	v_pk_mul_f32 v[92:93], v[68:69], v[68:69]
	v_mul_f32_e32 v94, v65, v65
	v_mul_f32_e32 v96, v63, v63
	v_pk_mul_f32 v[98:99], v[54:55], v[54:55]
; __device__ __forceinline__ unsigned cvt_pk_bf16(float lo, float hi) { unsigned r; asm volatile("v_cvt_pk_bf16_f32 %0, %1, %2" : "=v"(r) : "v"(lo), "v"(hi)); return r; }
; __device__ __forceinline__ float bf_lo(unsigned w) { return __uint_as_float(w << 16); }
; __device__ __forceinline__ float bf_hi(unsigned w) { return __uint_as_float(w & 0xffff0000u); }
; __device__ __forceinline__ void phase_mid(const Params& p, int gw, int NGW, int lane) {
;     ...
;         for (int j = 0; j < 16; ++j) { const u32x2 mw = mr[64 * j]; const f32x4 mo = {bf_lo(mw.x), bf_hi(mw.x), bf_lo(mw.y), bf_hi(mw.y)}; h[j] = xr[64 * j] + mo * r1 * g1p[64 * j]; ss += (h[j][0] * h[j][0] + h[j][1] * h[j][1]) + (h[j][2] * h[j][2] + h[j][3] * h[j][3]); }
;         const float r2 = rsqrtf(wave_sum(ss) * (1.f / DM) + EPSN);
;         u32x2* ho = (u32x2*)(H1 + (size_t)row * DM) + lane; u32x2* co = (u32x2*)(Cb + (size_t)row * DM) + lane;
;         asm volatile("" : "+v"(ho), "+v"(co));
; #pragma unroll
;         for (int j = 0; j < 16; ++j) { { u32x2 hw; hw.x = cvt_pk_bf16(h[j][0], h[j][1]); hw.y = cvt_pk_bf16(h[j][2], h[j][3]); ho[64 * j] = hw; } const f32x4 c = h[j] * r2 * g2p[64 * j]; u32x2 w; w.x = cvt_pk_bf16(c[0], c[1]); w.y = cvt_pk_bf16(c[2], c[3]); co[64 * j] = w; }
	v_pk_mul_f32 v[100:101], v[56:57], v[56:57]
	v_mul_f32_e32 v102, v53, v53
	v_mul_f32_e32 v104, v51, v51
	v_pk_mul_f32 v[106:107], v[40:41], v[40:41]
	v_pk_mul_f32 v[108:109], v[42:43], v[42:43]
	v_mul_f32_e32 v110, v39, v39
	v_mul_f32_e32 v112, v37, v37
	v_pk_mul_f32 v[114:115], v[28:29], v[28:29]
	v_pk_mul_f32 v[116:117], v[30:31], v[30:31]
	v_mul_f32_e32 v118, v27, v27
	v_mul_f32_e32 v120, v21, v21
	v_cvt_pk_bf16_f32 v122, v198, v199
	v_cvt_pk_bf16_f32 v123, v232, v233
	v_pk_mov_b32 v[124:125], v[82:83], v[80:81] op_sel:[1,0]
	v_mov_b32_e32 v83, v81
	v_pk_mov_b32 v[80:81], v[86:87], v[84:85] op_sel:[1,0]
	v_mov_b32_e32 v87, v85
	global_store_dwordx2 v[24:25], v[122:123], off
	v_pk_mov_b32 v[126:127], v[92:93], v[90:91] op_sel:[1,0]
	v_mov_b32_e32 v93, v91
	v_pk_fma_f32 v[90:91], v[64:65], v[64:65], v[94:95] op_sel_hi:[1,1,0]
	v_pk_fma_f32 v[94:95], v[62:63], v[62:63], v[96:97] op_sel_hi:[1,1,0]
	v_pk_mov_b32 v[96:97], v[100:101], v[98:99] op_sel:[1,0]
	v_mov_b32_e32 v101, v99
	v_pk_fma_f32 v[98:99], v[52:53], v[52:53], v[102:103] op_sel_hi:[1,1,0]
	v_pk_fma_f32 v[102:103], v[50:51], v[50:51], v[104:105] op_sel_hi:[1,1,0]
	v_pk_mov_b32 v[104:105], v[108:109], v[106:107] op_sel:[1,0]
	v_mov_b32_e32 v109, v107
	v_pk_fma_f32 v[106:107], v[38:39], v[38:39], v[110:111] op_sel_hi:[1,1,0]
	v_pk_fma_f32 v[110:111], v[36:37], v[36:37], v[112:113] op_sel_hi:[1,1,0]
	v_pk_mov_b32 v[112:113], v[116:117], v[114:115] op_sel:[1,0]
	v_mov_b32_e32 v117, v115
	v_pk_fma_f32 v[114:115], v[26:27], v[26:27], v[118:119] op_sel_hi:[1,1,0]
	v_pk_fma_f32 v[118:119], v[20:21], v[20:21], v[120:121] op_sel_hi:[1,1,0]
	v_pk_add_f32 v[120:121], v[124:125], v[82:83]
	v_pk_add_f32 v[86:87], v[80:81], v[86:87]
	global_load_dwordx4 v[80:83], v176, s[24:25]
	global_load_dwordx4 v[122:125], v176, s[24:25] offset:1024
	global_load_dwordx4 v[148:151], v176, s[24:25] offset:2048
	global_load_dwordx4 v[152:155], v176, s[24:25] offset:3072
	v_add_u32_e32 v172, 0x1000, v176
	global_load_dwordx4 v[160:163], v172, s[24:25]
	global_load_dwordx4 v[168:171], v172, s[24:25] offset:1024
	global_load_dwordx4 v[180:183], v172, s[24:25] offset:2048
	global_load_dwordx4 v[184:187], v172, s[24:25] offset:3072
	v_add_u32_e32 v173, 0x2000, v176
	global_load_dwordx4 v[194:197], v173, s[24:25]
	global_load_dwordx4 v[204:207], v173, s[24:25] offset:1024
	global_load_dwordx4 v[208:211], v173, s[24:25] offset:2048
	global_load_dwordx4 v[212:215], v173, s[24:25] offset:3072
	v_add_u32_e32 v188, 0x3000, v176
	global_load_dwordx4 v[216:219], v188, s[24:25]
	global_load_dwordx4 v[224:227], v188, s[24:25] offset:1024
	global_load_dwordx4 v[238:241], v188, s[24:25] offset:2048
	global_load_dwordx4 v[242:245], v188, s[24:25] offset:3072
	v_mul_f32_e32 v44, v203, v203
	v_mul_f32_e32 v88, v237, v237
	v_mul_f32_e32 v128, v72, v72
	v_mul_f32_e32 v129, v73, v73
	v_mul_f32_e32 v130, v70, v70
	v_mul_f32_e32 v131, v71, v71
	v_pk_fma_f32 v[84:85], v[202:203], v[202:203], v[44:45] op_sel_hi:[1,1,0]
	v_pk_fma_f32 v[88:89], v[236:237], v[236:237], v[88:89] op_sel_hi:[1,1,0]
	v_pk_add_f32 v[96:97], v[96:97], v[100:101]
	v_pk_add_f32 v[100:101], v[104:105], v[108:109]
	v_pk_add_f32 v[108:109], v[120:121], v[120:121] op_sel:[0,1] op_sel_hi:[1,0]
	v_pk_add_f32 v[86:87], v[86:87], v[86:87] op_sel:[0,1] op_sel_hi:[1,0]
	v_mov_b32_e32 v85, v130
	v_mov_b32_e32 v89, v131
	v_mov_b32_e32 v109, v128
	v_mov_b32_e32 v87, v129
	v_pk_add_f32 v[84:85], v[84:85], v[88:89]
	v_pk_add_f32 v[86:87], v[108:109], v[86:87]
	v_pk_add_f32 v[92:93], v[126:127], v[92:93]
	v_pk_add_f32 v[84:85], v[86:87], v[84:85]
	v_mul_f32_e32 v132, v60, v60
	v_mul_f32_e32 v133, v61, v61
	v_mul_f32_e32 v134, v58, v58
	v_mul_f32_e32 v135, v59, v59
	v_pk_add_f32 v[88:89], v[92:93], v[92:93] op_sel:[0,1] op_sel_hi:[1,0]
	v_pk_add_f32 v[84:85], v[84:85], v[84:85] op_sel:[0,1] op_sel_hi:[1,0]
	v_mov_b32_e32 v91, v134
	v_mov_b32_e32 v95, v135
	v_mov_b32_e32 v89, v133
	v_mov_b32_e32 v85, v132
	v_pk_add_f32 v[90:91], v[90:91], v[94:95]
	v_pk_add_f32 v[84:85], v[84:85], v[88:89]
	v_pk_fma_f32 v[32:33], v[146:147], v[190:191], v[138:139]
	v_pk_add_f32 v[84:85], v[84:85], v[90:91]
	v_pk_fma_f32 v[34:35], v[144:145], v[222:223], v[136:137]
	v_mul_f32_e32 v136, v48, v48
	v_mul_f32_e32 v137, v49, v49
	v_mul_f32_e32 v138, v46, v46
	v_mul_f32_e32 v139, v47, v47
	v_pk_add_f32 v[92:93], v[96:97], v[96:97] op_sel:[0,1] op_sel_hi:[1,0]
	v_pk_add_f32 v[84:85], v[84:85], v[84:85] op_sel:[0,1] op_sel_hi:[1,0]
	v_mov_b32_e32 v99, v138
	v_mov_b32_e32 v103, v139
	v_mov_b32_e32 v93, v137
	v_mov_b32_e32 v85, v136
	v_pk_add_f32 v[94:95], v[98:99], v[102:103]
	v_pk_add_f32 v[84:85], v[84:85], v[92:93]
	v_mul_f32_e32 v140, v34, v34
	v_pk_add_f32 v[84:85], v[84:85], v[94:95]
	v_mul_f32_e32 v141, v35, v35
	v_mul_f32_e32 v142, v32, v32
	v_mul_f32_e32 v143, v33, v33
	v_pk_add_f32 v[96:97], v[100:101], v[100:101] op_sel:[0,1] op_sel_hi:[1,0]
	v_pk_add_f32 v[84:85], v[84:85], v[84:85] op_sel:[0,1] op_sel_hi:[1,0]
	v_mov_b32_e32 v107, v142
	v_mov_b32_e32 v111, v143
	v_mov_b32_e32 v97, v141
	v_mov_b32_e32 v85, v140
	v_pk_add_f32 v[98:99], v[106:107], v[110:111]
	v_pk_add_f32 v[84:85], v[84:85], v[96:97]
	v_pk_fma_f32 v[16:17], v[166:167], v[230:231], v[158:159]
	v_pk_fma_f32 v[18:19], v[164:165], v[228:229], v[156:157]
	v_pk_add_f32 v[104:105], v[112:113], v[116:117]
	v_pk_add_f32 v[84:85], v[84:85], v[98:99]
	v_mul_f32_e32 v144, v18, v18
	v_mul_f32_e32 v145, v19, v19
	v_mul_f32_e32 v146, v16, v16
	v_mul_f32_e32 v147, v17, v17
	v_pk_add_f32 v[100:101], v[104:105], v[104:105] op_sel:[0,1] op_sel_hi:[1,0]
	v_pk_add_f32 v[84:85], v[84:85], v[84:85] op_sel:[0,1] op_sel_hi:[1,0]
	v_mov_b32_e32 v115, v146
	v_mov_b32_e32 v119, v147
	v_mov_b32_e32 v101, v145
	v_mov_b32_e32 v85, v144
	v_pk_add_f32 v[102:103], v[114:115], v[118:119]
	v_pk_add_f32 v[84:85], v[84:85], v[100:101]
	s_nop 0
	v_pk_add_f32 v[84:85], v[84:85], v[102:103]
	s_nop 0
	v_add_f32_e32 v44, v84, v85
	ds_bpermute_b32 v84, v45, v44
	s_waitcnt lgkmcnt(0)
; __device__ __forceinline__ unsigned cvt_pk_bf16(float lo, float hi) { unsigned r; asm volatile("v_cvt_pk_bf16_f32 %0, %1, %2" : "=v"(r) : "v"(lo), "v"(hi)); return r; }
; __device__ __forceinline__ void phase_mid(const Params& p, int gw, int NGW, int lane) {
;     ...
;         const float r2 = rsqrtf(wave_sum(ss) * (1.f / DM) + EPSN);
;         u32x2* ho = (u32x2*)(H1 + (size_t)row * DM) + lane; u32x2* co = (u32x2*)(Cb + (size_t)row * DM) + lane;
;         asm volatile("" : "+v"(ho), "+v"(co));
; #pragma unroll
;         for (int j = 0; j < 16; ++j) { { u32x2 hw; hw.x = cvt_pk_bf16(h[j][0], h[j][1]); hw.y = cvt_pk_bf16(h[j][2], h[j][3]); ho[64 * j] = hw; } const f32x4 c = h[j] * r2 * g2p[64 * j]; u32x2 w; w.x = cvt_pk_bf16(c[0], c[1]); w.y = cvt_pk_bf16(c[2], c[3]); co[64 * j] = w; }
	v_add_f32_e32 v44, v44, v84
	ds_bpermute_b32 v84, v74, v44
	s_waitcnt lgkmcnt(0)
	v_add_f32_e32 v44, v44, v84
	ds_bpermute_b32 v84, v75, v44
	s_waitcnt lgkmcnt(0)
	v_add_f32_e32 v44, v44, v84
	ds_bpermute_b32 v84, v76, v44
	s_waitcnt lgkmcnt(0)
	v_add_f32_e32 v44, v44, v84
	ds_bpermute_b32 v84, v77, v44
	s_waitcnt lgkmcnt(0)
	v_add_f32_e32 v44, v44, v84
	ds_bpermute_b32 v84, v78, v44
	s_waitcnt lgkmcnt(0)
	v_add_f32_e32 v44, v44, v84
	v_fmamk_f32 v44, v44, 0x39800000, v79
	v_mul_f32_e32 v84, 0x4b800000, v44
	v_cmp_gt_f32_e32 vcc, s8, v44
	s_nop 1
	v_cndmask_b32_e32 v44, v44, v84, vcc
	v_rsq_f32_e32 v44, v44
	s_nop 0
	v_mul_f32_e32 v84, 0x45800000, v44
	v_cndmask_b32_e32 v44, v44, v84, vcc
	v_pk_mul_f32 v[84:85], v[198:199], v[44:45] op_sel_hi:[1,0]
	v_pk_mul_f32 v[86:87], v[232:233], v[44:45] op_sel_hi:[1,0]
	s_waitcnt vmcnt(0)
	v_pk_mul_f32 v[80:81], v[80:81], v[84:85]
	v_pk_mul_f32 v[82:83], v[82:83], v[86:87]
	v_cvt_pk_bf16_f32 v80, v80, v81
	v_pk_mul_f32 v[84:85], v[200:201], v[44:45] op_sel_hi:[1,0]
	v_cvt_pk_bf16_f32 v81, v82, v83
	global_store_dwordx2 v[22:23], v[80:81], off
	v_cvt_pk_bf16_f32 v80, v200, v201
	v_cvt_pk_bf16_f32 v81, v234, v235
	global_store_dwordx2 v[24:25], v[80:81], off offset:512
	v_mov_b64_e32 v[80:81], v[122:123]
	v_mov_b64_e32 v[82:83], v[124:125]
	v_pk_mul_f32 v[86:87], v[234:235], v[44:45] op_sel_hi:[1,0]
	v_pk_mul_f32 v[80:81], v[80:81], v[84:85]
	v_pk_mul_f32 v[82:83], v[82:83], v[86:87]
	v_cvt_pk_bf16_f32 v80, v80, v81
	v_pk_mul_f32 v[84:85], v[202:203], v[44:45] op_sel_hi:[1,0]
	v_cvt_pk_bf16_f32 v81, v82, v83
	global_store_dwordx2 v[22:23], v[80:81], off offset:512
	v_cvt_pk_bf16_f32 v80, v202, v203
	v_cvt_pk_bf16_f32 v81, v236, v237
	global_store_dwordx2 v[24:25], v[80:81], off offset:1024
	v_mov_b64_e32 v[80:81], v[148:149]
	v_mov_b64_e32 v[82:83], v[150:151]
	v_pk_mul_f32 v[86:87], v[236:237], v[44:45] op_sel_hi:[1,0]
	v_pk_mul_f32 v[80:81], v[80:81], v[84:85]
	v_pk_mul_f32 v[82:83], v[82:83], v[86:87]
	v_cvt_pk_bf16_f32 v80, v80, v81
	v_add_co_u32_e32 v84, vcc, s9, v14
	v_cvt_pk_bf16_f32 v81, v82, v83
	global_store_dwordx2 v[22:23], v[80:81], off offset:1024
	v_cvt_pk_bf16_f32 v80, v72, v73
	v_cvt_pk_bf16_f32 v81, v70, v71
	global_store_dwordx2 v[24:25], v[80:81], off offset:1536
	v_mov_b64_e32 v[80:81], v[152:153]
	v_mov_b64_e32 v[82:83], v[154:155]
	v_pk_mul_f32 v[72:73], v[72:73], v[44:45] op_sel_hi:[1,0]
	v_pk_mul_f32 v[70:71], v[70:71], v[44:45] op_sel_hi:[1,0]
	v_addc_co_u32_e32 v85, vcc, 0, v15, vcc
	v_pk_mul_f32 v[70:71], v[70:71], v[82:83]
	v_pk_mul_f32 v[72:73], v[72:73], v[80:81]
	s_nop 0
	v_cvt_pk_bf16_f32 v72, v72, v73
	v_cvt_pk_bf16_f32 v73, v70, v71
	global_store_dwordx2 v[22:23], v[72:73], off offset:1536
	v_cvt_pk_bf16_f32 v70, v68, v69
	v_cvt_pk_bf16_f32 v71, v66, v67
	global_store_dwordx2 v[24:25], v[70:71], off offset:2048
	v_mov_b64_e32 v[70:71], v[160:161]
	v_mov_b64_e32 v[72:73], v[162:163]
	v_pk_mul_f32 v[68:69], v[68:69], v[44:45] op_sel_hi:[1,0]
	v_pk_mul_f32 v[66:67], v[66:67], v[44:45] op_sel_hi:[1,0]
	v_pk_mul_f32 v[68:69], v[68:69], v[70:71]
	v_pk_mul_f32 v[66:67], v[66:67], v[72:73]
	v_cvt_pk_bf16_f32 v68, v68, v69
	s_nop 0
	v_cvt_pk_bf16_f32 v69, v66, v67
	global_store_dwordx2 v[22:23], v[68:69], off offset:2048
	v_cvt_pk_bf16_f32 v66, v64, v65
	v_cvt_pk_bf16_f32 v67, v62, v63
	global_store_dwordx2 v[24:25], v[66:67], off offset:2560
	v_mov_b64_e32 v[66:67], v[168:169]
	v_mov_b64_e32 v[68:69], v[170:171]
	v_pk_mul_f32 v[64:65], v[64:65], v[44:45] op_sel_hi:[1,0]
	v_pk_mul_f32 v[62:63], v[62:63], v[44:45] op_sel_hi:[1,0]
	v_pk_mul_f32 v[64:65], v[64:65], v[66:67]
	v_pk_mul_f32 v[62:63], v[62:63], v[68:69]
	v_cvt_pk_bf16_f32 v64, v64, v65
	s_nop 0
	v_cvt_pk_bf16_f32 v65, v62, v63
	global_store_dwordx2 v[22:23], v[64:65], off offset:2560
	v_cvt_pk_bf16_f32 v62, v60, v61
	v_cvt_pk_bf16_f32 v63, v58, v59
	global_store_dwordx2 v[24:25], v[62:63], off offset:3072
	v_mov_b64_e32 v[62:63], v[180:181]
	v_mov_b64_e32 v[64:65], v[182:183]
	v_pk_mul_f32 v[60:61], v[60:61], v[44:45] op_sel_hi:[1,0]
	v_pk_mul_f32 v[58:59], v[58:59], v[44:45] op_sel_hi:[1,0]
	v_pk_mul_f32 v[60:61], v[60:61], v[62:63]
	v_pk_mul_f32 v[58:59], v[58:59], v[64:65]
	v_cvt_pk_bf16_f32 v60, v60, v61
	v_add_co_u32_e32 v62, vcc, s3, v14
	v_cvt_pk_bf16_f32 v61, v58, v59
	global_store_dwordx2 v[22:23], v[60:61], off offset:3072
	v_cvt_pk_bf16_f32 v58, v56, v57
	v_cvt_pk_bf16_f32 v59, v54, v55
	global_store_dwordx2 v[24:25], v[58:59], off offset:3584
	v_mov_b64_e32 v[58:59], v[184:185]
	v_mov_b64_e32 v[60:61], v[186:187]
	v_addc_co_u32_e32 v63, vcc, 0, v15, vcc
	v_add_co_u32_e32 v64, vcc, s9, v24
	v_pk_mul_f32 v[54:55], v[54:55], v[44:45] op_sel_hi:[1,0]
	s_nop 0
	v_addc_co_u32_e32 v65, vcc, 0, v25, vcc
; __device__ __forceinline__ unsigned cvt_pk_bf16(float lo, float hi) { unsigned r; asm volatile("v_cvt_pk_bf16_f32 %0, %1, %2" : "=v"(r) : "v"(lo), "v"(hi)); return r; }
; __device__ __forceinline__ void phase_mid(const Params& p, int gw, int NGW, int lane) {
;     ...
;         for (int j = 0; j < 16; ++j) { { u32x2 hw; hw.x = cvt_pk_bf16(h[j][0], h[j][1]); hw.y = cvt_pk_bf16(h[j][2], h[j][3]); ho[64 * j] = hw; } const f32x4 c = h[j] * r2 * g2p[64 * j]; u32x2 w; w.x = cvt_pk_bf16(c[0], c[1]); w.y = cvt_pk_bf16(c[2], c[3]); co[64 * j] = w; }
	v_pk_mul_f32 v[24:25], v[56:57], v[44:45] op_sel_hi:[1,0]
	v_pk_mul_f32 v[54:55], v[54:55], v[60:61]
	v_pk_mul_f32 v[24:25], v[24:25], v[58:59]
	v_add_co_u32_e32 v58, vcc, s9, v22
	v_cvt_pk_bf16_f32 v24, v24, v25
	v_cvt_pk_bf16_f32 v25, v54, v55
	global_store_dwordx2 v[22:23], v[24:25], off offset:3584
	v_cvt_pk_bf16_f32 v24, v52, v53
	v_cvt_pk_bf16_f32 v25, v50, v51
	global_store_dwordx2 v[64:65], v[24:25], off
	v_mov_b64_e32 v[54:55], v[194:195]
	v_mov_b64_e32 v[56:57], v[196:197]
	v_addc_co_u32_e32 v59, vcc, 0, v23, vcc
	v_pk_mul_f32 v[22:23], v[52:53], v[44:45] op_sel_hi:[1,0]
	v_pk_mul_f32 v[24:25], v[50:51], v[44:45] op_sel_hi:[1,0]
	v_add_co_u32_e32 v14, vcc, s16, v14
	v_pk_mul_f32 v[22:23], v[22:23], v[54:55]
	v_pk_mul_f32 v[24:25], v[24:25], v[56:57]
	v_cvt_pk_bf16_f32 v22, v22, v23
	v_addc_co_u32_e32 v15, vcc, 0, v15, vcc
	v_cvt_pk_bf16_f32 v23, v24, v25
	global_store_dwordx2 v[58:59], v[22:23], off
	v_cvt_pk_bf16_f32 v22, v48, v49
	v_cvt_pk_bf16_f32 v23, v46, v47
	global_store_dwordx2 v[64:65], v[22:23], off offset:512
	v_mov_b64_e32 v[22:23], v[204:205]
	v_mov_b64_e32 v[24:25], v[206:207]
	v_pk_mul_f32 v[48:49], v[48:49], v[44:45] op_sel_hi:[1,0]
	v_pk_mul_f32 v[46:47], v[46:47], v[44:45] op_sel_hi:[1,0]
	v_pk_mul_f32 v[22:23], v[48:49], v[22:23]
	v_pk_mul_f32 v[24:25], v[46:47], v[24:25]
	v_cvt_pk_bf16_f32 v22, v22, v23
	s_nop 0
	v_cvt_pk_bf16_f32 v23, v24, v25
	global_store_dwordx2 v[58:59], v[22:23], off offset:512
	v_cvt_pk_bf16_f32 v22, v42, v43
	v_cvt_pk_bf16_f32 v23, v40, v41
	global_store_dwordx2 v[64:65], v[22:23], off offset:1024
	v_mov_b64_e32 v[22:23], v[208:209]
	v_mov_b64_e32 v[24:25], v[210:211]
	v_pk_mul_f32 v[42:43], v[42:43], v[44:45] op_sel_hi:[1,0]
	v_pk_mul_f32 v[40:41], v[40:41], v[44:45] op_sel_hi:[1,0]
	v_pk_mul_f32 v[22:23], v[42:43], v[22:23]
	v_pk_mul_f32 v[24:25], v[40:41], v[24:25]
	v_cvt_pk_bf16_f32 v22, v22, v23
	s_nop 0
	v_cvt_pk_bf16_f32 v23, v24, v25
	global_store_dwordx2 v[58:59], v[22:23], off offset:1024
	v_cvt_pk_bf16_f32 v22, v38, v39
	v_cvt_pk_bf16_f32 v23, v36, v37
	global_store_dwordx2 v[64:65], v[22:23], off offset:1536
	v_mov_b64_e32 v[22:23], v[212:213]
	v_mov_b64_e32 v[24:25], v[214:215]
	v_pk_mul_f32 v[38:39], v[38:39], v[44:45] op_sel_hi:[1,0]
	v_pk_mul_f32 v[36:37], v[36:37], v[44:45] op_sel_hi:[1,0]
	v_pk_mul_f32 v[22:23], v[38:39], v[22:23]
	v_pk_mul_f32 v[24:25], v[36:37], v[24:25]
	v_cvt_pk_bf16_f32 v22, v22, v23
	s_nop 0
	v_cvt_pk_bf16_f32 v23, v24, v25
	global_store_dwordx2 v[58:59], v[22:23], off offset:1536
	v_cvt_pk_bf16_f32 v22, v34, v35
	v_cvt_pk_bf16_f32 v23, v32, v33
	global_store_dwordx2 v[64:65], v[22:23], off offset:2048
	v_mov_b64_e32 v[22:23], v[216:217]
	v_mov_b64_e32 v[24:25], v[218:219]
	v_pk_mul_f32 v[34:35], v[34:35], v[44:45] op_sel_hi:[1,0]
	v_pk_mul_f32 v[32:33], v[32:33], v[44:45] op_sel_hi:[1,0]
	v_pk_mul_f32 v[22:23], v[34:35], v[22:23]
	v_pk_mul_f32 v[24:25], v[32:33], v[24:25]
	v_cvt_pk_bf16_f32 v22, v22, v23
	s_nop 0
	v_cvt_pk_bf16_f32 v23, v24, v25
	global_store_dwordx2 v[58:59], v[22:23], off offset:2048
	v_cvt_pk_bf16_f32 v22, v30, v31
	v_cvt_pk_bf16_f32 v23, v28, v29
	global_store_dwordx2 v[64:65], v[22:23], off offset:2560
	v_mov_b64_e32 v[22:23], v[224:225]
	v_mov_b64_e32 v[24:25], v[226:227]
	v_pk_mul_f32 v[30:31], v[30:31], v[44:45] op_sel_hi:[1,0]
	v_pk_mul_f32 v[28:29], v[28:29], v[44:45] op_sel_hi:[1,0]
	v_pk_mul_f32 v[22:23], v[30:31], v[22:23]
	v_pk_mul_f32 v[24:25], v[28:29], v[24:25]
	v_cvt_pk_bf16_f32 v22, v22, v23
	s_nop 0
	v_cvt_pk_bf16_f32 v23, v24, v25
	global_store_dwordx2 v[58:59], v[22:23], off offset:2560
	v_cvt_pk_bf16_f32 v22, v26, v27
	v_cvt_pk_bf16_f32 v23, v20, v21
	global_store_dwordx2 v[64:65], v[22:23], off offset:3072
	v_mov_b64_e32 v[22:23], v[238:239]
	v_mov_b64_e32 v[24:25], v[240:241]
	v_pk_mul_f32 v[26:27], v[26:27], v[44:45] op_sel_hi:[1,0]
	v_pk_mul_f32 v[20:21], v[20:21], v[44:45] op_sel_hi:[1,0]
	v_pk_mul_f32 v[22:23], v[26:27], v[22:23]
	v_pk_mul_f32 v[20:21], v[20:21], v[24:25]
	v_cvt_pk_bf16_f32 v22, v22, v23
	s_nop 0
	v_cvt_pk_bf16_f32 v23, v20, v21
	global_store_dwordx2 v[58:59], v[22:23], off offset:3072
	v_cvt_pk_bf16_f32 v20, v18, v19
	v_cvt_pk_bf16_f32 v21, v16, v17
	global_store_dwordx2 v[64:65], v[20:21], off offset:3584
	v_mov_b64_e32 v[20:21], v[242:243]
	v_mov_b64_e32 v[22:23], v[244:245]
	v_pk_mul_f32 v[14:15], v[18:19], v[44:45] op_sel_hi:[1,0]
	v_pk_mul_f32 v[16:17], v[16:17], v[44:45] op_sel_hi:[1,0]
	v_pk_mul_f32 v[14:15], v[14:15], v[20:21]
	v_pk_mul_f32 v[16:17], v[16:17], v[22:23]
	v_cvt_pk_bf16_f32 v14, v14, v15
	s_nop 0
	v_cvt_pk_bf16_f32 v15, v16, v17
	global_store_dwordx2 v[58:59], v[14:15], off offset:3584
	s_cbranch_scc1 .LBB0_711
